# in-GEMM epilogues: per-row sum-of-squares loads cached in spare VGPRs across a workgroup's units (same row tile), removing a load round trip per tile
# speedup vs baseline: 1.0154x; 1.0098x over previous
.LBB0_272:
	s_mov_b32 s98, 0
	s_and_b64 s[8:9], s[52:53], exec
	s_cselect_b32 s8, s17, 0x8000000
	s_add_u32 s48, s84, s8
	s_addc_u32 s49, s85, 0
	s_and_b64 s[8:9], s[52:53], exec
	s_cselect_b32 s8, 0x8000000, s17
	s_add_u32 s50, s84, s8
	s_addc_u32 s51, s85, 0
	s_lshl_b32 s30, s64, 14
	s_lshl_b64 s[8:9], s[30:31], 2
	v_readlane_b32 s10, v242, 3
	v_readlane_b32 s11, v242, 4
	s_add_u32 s42, s10, s8
	v_mov_b32_e32 v5, v1
	s_addc_u32 s43, s11, s9
	s_andn2_b64 vcc, exec, s[0:1]
	v_readfirstlane_b32 s8, v5
	s_cbranch_vccnz .LBB0_330
	v_bfe_i32 v3, v5, 27, 1
	v_lshlrev_b32_e32 v6, 4, v5
	v_lshrrev_b32_e32 v3, 22, v3
	v_ashrrev_i32_e32 v2, 31, v5
	v_add_u32_e32 v3, v6, v3
	v_lshrrev_b32_e32 v2, 26, v2
	v_and_b32_e32 v3, 0xfffffc00, v3
	v_add_u32_e32 v2, v5, v2
	v_sub_u32_e32 v3, v6, v3
	v_ashrrev_i32_e32 v2, 6, v2
	v_lshrrev_b32_e32 v4, 4, v3
	v_bitop3_b32 v4, v4, v3, 32 bitop3:0x6c
	v_lshlrev_b32_e32 v3, 3, v2
	v_and_b32_e32 v7, -16, v3
	v_ashrrev_i32_e32 v3, 31, v4
	v_lshrrev_b32_e32 v3, 26, v3
	v_add_u32_e32 v8, v4, v3
	v_ashrrev_i32_e32 v3, 6, v8
	v_and_b32_e32 v8, 0xc0, v8
	v_sub_u32_e32 v4, v4, v8
	v_lshlrev_b32_e32 v9, 5, v2
	v_ashrrev_i16_sdwa v4, v193, sext(v4) dst_sel:DWORD dst_unused:UNUSED_PAD src0_sel:DWORD src1_sel:BYTE_0
	v_and_b32_e32 v9, 32, v9
	v_bfe_i32 v4, v4, 0, 16
	v_add_u32_e32 v7, v3, v7
	v_and_b32_e32 v11, 3, v3
	v_add_lshl_u32 v9, v9, v4, 1
	v_lshlrev_b32_e32 v8, 1, v7
	v_lshrrev_b32_e32 v10, 2, v7
	v_and_or_b32 v11, v7, s25, v11
	v_lshl_add_u32 v130, v7, 12, v9
	v_add_u32_e32 v7, 0x2000, v6
	v_ashrrev_i32_e32 v6, 31, v7
	v_lshrrev_b32_e32 v6, 22, v6
	v_and_b32_e32 v8, 24, v8
	v_and_b32_e32 v10, 4, v10
	v_add_u32_e32 v6, v7, v6
	v_or3_b32 v8, v11, v10, v8
	v_ashrrev_i32_e32 v6, 10, v6
	v_lshl_add_u32 v132, v8, 12, v9
	v_mul_i32_i24_e32 v8, 0x400, v6
	v_sub_u32_e32 v7, v7, v8
	v_lshrrev_b32_e32 v8, 4, v7
	s_and_b64 s[10:11], s[52:53], exec
	v_bitop3_b32 v8, v8, v7, 32 bitop3:0x6c
	v_lshlrev_b32_e32 v7, 3, v6
	s_cselect_b32 s9, 0, 0x1000000
	v_and_b32_e32 v9, -16, v7
	v_ashrrev_i32_e32 v7, 31, v8
	s_add_u32 s30, s94, s9
	v_lshrrev_b32_e32 v7, 26, v7
	s_addc_u32 s65, s95, 0
	v_add_u32_e32 v10, v8, v7
	s_ashr_i32 s12, s8, 6
	s_ashr_i32 s9, s8, 8
	v_ashrrev_i32_e32 v7, 6, v10
	v_and_b32_e32 v10, 0xc0, v10
	s_lshl_b32 s80, s12, 10
	v_add_u32_e32 v9, v7, v9
	v_sub_u32_e32 v8, v8, v10
	s_add_u32 s10, s30, s26
	v_lshlrev_b32_e32 v11, 5, v6
	v_ashrrev_i16_sdwa v8, v193, sext(v8) dst_sel:DWORD dst_unused:UNUSED_PAD src0_sel:DWORD src1_sel:BYTE_0
	v_lshlrev_b32_e32 v10, 1, v9
	v_lshrrev_b32_e32 v12, 2, v9
	v_and_b32_e32 v13, 3, v7
	s_addc_u32 s11, s65, s27
	s_add_i32 s81, s80, 0
	v_and_b32_e32 v11, 32, v11
	v_bfe_i32 v8, v8, 0, 16
	v_and_b32_e32 v10, 24, v10
	v_and_b32_e32 v12, 4, v12
	v_and_or_b32 v13, v9, s25, v13
	s_add_i32 m0, s81, 0x10000
	v_or3_b32 v10, v13, v12, v10
	v_add_lshl_u32 v11, v11, v8, 1
	global_load_lds_dwordx4 v132, s[10:11]
	s_add_i32 m0, s81, 0x12000
	v_lshl_add_u32 v136, v10, 12, v11
	s_add_u32 s28, s10, 0x80000
	global_load_lds_dwordx4 v136, s[10:11]
	s_addc_u32 s29, s11, 0
	s_add_i32 m0, s81, 0x14000
	v_lshl_add_u32 v134, v9, 12, v11
	global_load_lds_dwordx4 v132, s[28:29]
	s_add_i32 m0, s81, 0x16000
	s_add_u32 s60, s48, s18
	s_addc_u32 s61, s49, s19
	s_add_i32 s82, s81, 0x2000
	global_load_lds_dwordx4 v136, s[28:29]
	s_mov_b32 m0, s81
	s_add_u32 s28, s60, 0x80000
	global_load_lds_dwordx4 v130, s[60:61]
	s_mov_b32 m0, s82
	s_addc_u32 s29, s61, 0
	s_add_i32 s83, s81, 0x4000
	global_load_lds_dwordx4 v134, s[60:61]
	s_mov_b32 m0, s83
	s_add_i32 s84, s81, 0x6000
	global_load_lds_dwordx4 v130, s[28:29]
	s_mov_b32 m0, s84
	s_cmp_eq_u32 s9, 1
	global_load_lds_dwordx4 v134, s[28:29]
	s_cselect_b64 s[54:55], -1, 0
	s_cmp_lg_u32 s9, 1
	s_cbranch_scc1 .LBB0_275
	s_barrier

.LBB0_293:
	v_lshl_add_u32 v142, s91, 8, v168
	v_ashrrev_i32_e32 v143, 31, v142
	v_lshl_add_u64 v[144:145], v[142:143], 2, s[42:43]
	s_add_u32 s99, s91, 1
	s_cmp_eq_u32 s98, s99
	s_cbranch_scc1 .Lssq_a_cached
	global_load_dword v243, v[144:145], off
	global_load_dword v244, v[144:145], off offset:64
	global_load_dword v245, v[144:145], off offset:128
	global_load_dword v246, v[144:145], off offset:192
	global_load_dword v247, v[144:145], off offset:512
	global_load_dword v248, v[144:145], off offset:576
	global_load_dword v249, v[144:145], off offset:640
	global_load_dword v250, v[144:145], off offset:704
	s_waitcnt vmcnt(0)
	s_mov_b32 s98, s99
.Lssq_a_cached:
	v_mov_b32_e32 v146, v243
	v_mov_b32_e32 v178, v244
	v_mov_b32_e32 v177, v245
	v_mov_b32_e32 v176, v246
	v_mov_b32_e32 v175, v247
	v_mov_b32_e32 v174, v248
	v_mov_b32_e32 v173, v249
	v_mov_b32_e32 v172, v250
	s_cmp_gt_i32 s87, 7
	s_cselect_b64 s[10:11], -1, 0
	s_cmp_lt_i32 s87, 8
	s_nop 0
	v_fmamk_f32 v144, v146, 0x3a000000, v192
	v_mul_f32_e32 v145, 0x4b800000, v144
	v_cmp_gt_f32_e32 vcc, s77, v144
	s_nop 1
	v_cndmask_b32_e32 v144, v144, v145, vcc
	v_rsq_f32_e32 v144, v144
	s_nop 0
	v_mul_f32_e32 v145, 0x45800000, v144
	v_cndmask_b32_e32 v146, v144, v145, vcc
	v_pk_mul_f32 v[150:151], v[128:129], v[146:147] op_sel_hi:[1,0]
	v_pk_mul_f32 v[164:165], v[126:127], v[146:147] op_sel_hi:[1,0]
	v_pk_mul_f32 v[152:153], v[124:125], v[146:147] op_sel_hi:[1,0]
	v_pk_mul_f32 v[166:167], v[122:123], v[146:147] op_sel_hi:[1,0]
	s_cbranch_scc1 .LBB0_295
	v_mul_f32_e32 v147, 0xbfb8aa3b, v167
	v_exp_f32_e32 v147, v147
	v_mul_f32_e32 v145, 0xbfb8aa3b, v166
	v_exp_f32_e32 v145, v145
	v_mul_f32_e32 v144, 0xbfb8aa3b, v164
	v_add_f32_e32 v147, 1.0, v147
	v_rcp_f32_e32 v149, v147
	v_mul_f32_e32 v147, 0xbfb8aa3b, v150
	v_add_f32_e32 v145, 1.0, v145
	v_exp_f32_e32 v147, v147
	v_rcp_f32_e32 v148, v145
	v_mul_f32_e32 v145, 0xbfb8aa3b, v165
	v_exp_f32_e32 v144, v144
	v_exp_f32_e32 v145, v145
	v_add_f32_e32 v147, 1.0, v147
	v_rcp_f32_e32 v180, v147
	v_mul_f32_e32 v147, 0xbfb8aa3b, v152
	v_add_f32_e32 v144, 1.0, v144
	v_add_f32_e32 v145, 1.0, v145
	v_exp_f32_e32 v147, v147
	v_rcp_f32_e32 v144, v144
	v_rcp_f32_e32 v145, v145
	v_pk_mul_f32 v[166:167], v[166:167], v[148:149]
	v_add_f32_e32 v147, 1.0, v147
	v_rcp_f32_e32 v182, v147
	v_mul_f32_e32 v147, 0xbfb8aa3b, v151
	v_pk_mul_f32 v[164:165], v[164:165], v[144:145]
	v_mul_f32_e32 v144, 0xbfb8aa3b, v153
	v_exp_f32_e32 v147, v147
	v_exp_f32_e32 v144, v144
	v_add_f32_e32 v147, 1.0, v147
	v_add_f32_e32 v144, 1.0, v144
	v_rcp_f32_e32 v181, v147
	v_rcp_f32_e32 v183, v144
	v_pk_mul_f32 v[150:151], v[150:151], v[180:181]
	v_pk_mul_f32 v[152:153], v[152:153], v[182:183]

.LBB0_567:
	s_mov_b32 s98, 0
	s_and_b64 s[8:9], s[30:31], exec
	s_cselect_b32 s12, 48, 32
	s_lshl_b32 s20, s12, 5
	v_mov_b32_e32 v2, v1
	s_cmp_lt_i32 s88, s20
	s_cselect_b64 s[8:9], -1, 0
	s_cmp_ge_i32 s88, s20
	v_readfirstlane_b32 s13, v2
	s_cbranch_scc1 .LBB0_569
	s_lshl_b32 s10, s12, 3
	v_cvt_f32_u32_e32 v4, s10
	s_lshl_b32 s11, s12, 2
	v_readlane_b32 s14, v240, 1
	s_or_b32 s11, s11, s14
	v_rcp_iflag_f32_e32 v4, v4
	s_sub_i32 s14, 0, s10
	v_readlane_b32 s15, v241, 15
	s_mul_i32 s11, s11, s15
	v_mul_f32_e32 v4, 0x4f7ffffe, v4
	v_cvt_u32_f32_e32 v4, v4
	v_readlane_b32 s15, v241, 16
	s_add_i32 s11, s11, s15
	s_abs_i32 s24, s11
	v_readfirstlane_b32 s25, v4
	s_mul_i32 s14, s14, s25
	s_mul_hi_u32 s14, s25, s14
	s_add_i32 s25, s25, s14
	s_mul_hi_u32 s14, s24, s25
	s_mul_i32 s25, s14, s10
	s_sub_i32 s24, s24, s25
	s_ashr_i32 s15, s11, 31
	s_add_i32 s26, s14, 1
	s_sub_i32 s25, s24, s10
	s_cmp_ge_u32 s24, s10
	s_cselect_b32 s14, s26, s14
	s_cselect_b32 s24, s25, s24
	s_add_i32 s25, s14, 1
	s_cmp_ge_u32 s24, s10
	s_cselect_b32 s14, s25, s14
	s_xor_b32 s14, s14, s15
	s_sub_i32 s14, s14, s15
	s_lshl_b32 s24, s14, 3
	s_sub_i32 s15, 32, s24
	s_min_i32 s25, s15, 8
	s_mul_i32 s14, s14, s10
	s_sext_i32_i16 s10, s25
	v_cvt_f32_i32_e32 v4, s10
	s_sub_i32 s14, s11, s14
	s_sext_i32_i16 s11, s14
	v_cvt_f32_i32_e32 v5, s11
	v_rcp_iflag_f32_e32 v6, v4
	s_xor_b32 s10, s11, s10
	s_ashr_i32 s10, s10, 30
	s_or_b32 s15, s10, 1
	v_mul_f32_e32 v6, v5, v6
	v_trunc_f32_e32 v6, v6
	v_fma_f32 v5, -v6, v4, v5
	v_cvt_i32_f32_e32 v6, v6
	v_cmp_ge_f32_e64 s[10:11], |v5|, |v4|
	s_and_b64 s[10:11], s[10:11], exec
	s_cselect_b32 s10, s15, 0
	v_readfirstlane_b32 s11, v6
	s_add_i32 s10, s11, s10
	s_sext_i32_i16 s15, s10
	s_mul_i32 s10, s10, s25
	s_sub_i32 s10, s14, s10
	s_sext_i32_i16 s10, s10
	s_add_i32 s14, s24, s10

.LBB0_637:
	v_lshl_add_u32 v186, s44, 8, v177
	v_or_b32_e32 v142, 16, v186
	v_ashrrev_i32_e32 v187, 31, v186
	v_ashrrev_i32_e32 v143, 31, v142
	v_or_b32_e32 v140, 32, v186
	v_lshl_add_u64 v[132:133], v[186:187], 2, s[48:49]
	v_lshl_add_u64 v[134:135], v[142:143], 2, s[48:49]
	v_ashrrev_i32_e32 v141, 31, v140
	v_or_b32_e32 v138, 48, v186
	s_nop 0
	s_nop 0
	v_lshl_add_u64 v[134:135], v[140:141], 2, s[48:49]
	v_ashrrev_i32_e32 v139, 31, v138
	s_nop 0
	v_lshl_add_u64 v[134:135], v[138:139], 2, s[48:49]
	s_nop 0
	s_nop 0
	s_nop 0
	s_nop 0
	s_add_u32 s99, s44, 1
	s_cmp_eq_u32 s98, s99
	s_cbranch_scc1 .Lssq_b_cached
	global_load_dword v243, v[132:133], off
	global_load_dword v244, v[132:133], off offset:64
	global_load_dword v245, v[132:133], off offset:128
	global_load_dword v246, v[132:133], off offset:192
	global_load_dword v247, v[132:133], off offset:512
	global_load_dword v248, v[132:133], off offset:576
	global_load_dword v249, v[132:133], off offset:640
	global_load_dword v250, v[132:133], off offset:704
	s_waitcnt vmcnt(0)
	s_mov_b32 s98, s99
.Lssq_b_cached:
	v_mov_b32_e32 v136, v243
	v_mov_b32_e32 v194, v244
	v_mov_b32_e32 v211, v245
	v_mov_b32_e32 v210, v246
	v_mov_b32_e32 v209, v247
	v_mov_b32_e32 v208, v248
	v_mov_b32_e32 v207, v249
	v_mov_b32_e32 v206, v250
	v_add_u32_e32 v188, 0x80, v186
	s_mov_b64 s[12:13], -1
	v_ashrrev_i32_e32 v189, 31, v188
	s_andn2_b64 vcc, exec, s[0:1]
	s_nop 0
	v_fmamk_f32 v133, v136, 0x3a000000, v200
	v_cmp_gt_f32_e64 s[0:1], s91, v133
	v_mul_f32_e32 v146, 0x4b800000, v133
	s_cbranch_vccz .LBB0_646
	v_cndmask_b32_e64 v132, v133, v146, s[0:1]
	v_rsq_f32_e32 v132, v132
	s_xor_b64 s[10:11], s[10:11], -1
	s_and_b64 vcc, exec, s[10:11]
	v_mul_f32_e32 v134, 0x45800000, v132
	v_cndmask_b32_e64 v132, v132, v134, s[0:1]
	s_mov_b64 s[0:1], -1
	s_cbranch_vccz .LBB0_640
	v_pk_mul_f32 v[150:151], v[128:129], v[132:133] op_sel_hi:[1,0]
	v_pk_mul_f32 v[154:155], v[124:125], v[132:133] op_sel_hi:[1,0]
	v_mul_f32_e32 v147, 0xbfb8aa3b, v150
	v_exp_f32_e32 v147, v147
	v_pk_mul_f32 v[148:149], v[130:131], v[132:133] op_sel_hi:[1,0]
	v_pk_mul_f32 v[152:153], v[126:127], v[132:133] op_sel_hi:[1,0]
	v_lshl_or_b32 v136, s9, 8, v176
	v_add_f32_e32 v147, 1.0, v147
	v_rcp_f32_e32 v147, v147
	v_ashrrev_i32_e32 v137, 31, v136
	v_lshl_add_u64 v[136:137], v[136:137], 1, s[26:27]
	v_lshlrev_b64 v[144:145], 12, v[186:187]
	v_mul_f32_e32 v147, v150, v147
	v_mul_f32_e32 v150, 0xbfb8aa3b, v154
	v_exp_f32_e32 v150, v150
	v_lshl_add_u64 v[144:145], v[136:137], 0, v[144:145]
	v_lshlrev_b64 v[142:143], 12, v[142:143]
	v_lshl_add_u64 v[142:143], v[136:137], 0, v[142:143]
	v_add_f32_e32 v150, 1.0, v150
	v_rcp_f32_e32 v150, v150
	v_lshlrev_b64 v[140:141], 12, v[140:141]
	v_lshl_add_u64 v[140:141], v[136:137], 0, v[140:141]
	v_lshlrev_b64 v[138:139], 12, v[138:139]
	v_mul_f32_e32 v150, v154, v150
	v_mul_f32_e32 v154, 0xbfb8aa3b, v151
	v_exp_f32_e32 v154, v154
	v_lshl_add_u64 v[138:139], v[136:137], 0, v[138:139]
	v_lshlrev_b64 v[134:135], 12, v[186:187]
	v_lshl_add_u64 v[134:135], v[136:137], 0, v[134:135]
	v_add_f32_e32 v154, 1.0, v154
	v_rcp_f32_e32 v154, v154
	s_mov_b64 s[0:1], 0x90000
	v_mul_f32_e32 v151, v151, v154
	v_mul_f32_e32 v154, 0xbfb8aa3b, v155
	v_exp_f32_e32 v154, v154
	s_nop 0
	v_add_f32_e32 v154, 1.0, v154
	v_rcp_f32_e32 v154, v154
	s_nop 0
	v_mul_f32_e32 v154, v155, v154
	v_mul_f32_e32 v155, 0xbfb8aa3b, v148
	v_exp_f32_e32 v155, v155
	s_nop 0
	v_add_f32_e32 v155, 1.0, v155
	v_rcp_f32_e32 v155, v155
	s_nop 0
	v_mul_f32_e32 v155, v148, v155
	v_mul_f32_e32 v148, 0xbfb8aa3b, v152
	v_exp_f32_e32 v148, v148
	s_nop 0
	v_add_f32_e32 v148, 1.0, v148
	v_rcp_f32_e32 v148, v148
	s_nop 0
	v_mul_f32_e32 v152, v152, v148
	v_mul_f32_e32 v148, 0xbfb8aa3b, v149
	v_exp_f32_e32 v148, v148
	s_nop 0
	v_add_f32_e32 v148, 1.0, v148
	v_rcp_f32_e32 v148, v148
	s_nop 0
	v_mul_f32_e32 v149, v149, v148
	v_mul_f32_e32 v148, 0xbfb8aa3b, v153
	v_exp_f32_e32 v148, v148
	s_nop 0
	v_add_f32_e32 v148, 1.0, v148
	v_rcp_f32_e32 v148, v148
	s_nop 0
	v_mul_f32_e32 v153, v153, v148
	v_cvt_pk_bf16_f32 v148, v147, v151
	v_cvt_pk_bf16_f32 v149, v155, v149
	v_cvt_pk_bf16_f32 v150, v150, v154
	v_cvt_pk_bf16_f32 v151, v152, v153
	global_store_dwordx4 v[144:145], v[148:151], off
	v_pk_mul_f32 v[154:155], v[92:93], v[132:133] op_sel_hi:[1,0]
	v_pk_mul_f32 v[152:153], v[94:95], v[132:133] op_sel_hi:[1,0]
	v_pk_mul_f32 v[150:151], v[96:97], v[132:133] op_sel_hi:[1,0]
	v_pk_mul_f32 v[148:149], v[98:99], v[132:133] op_sel_hi:[1,0]
	v_mul_f32_e32 v147, 0xbfb8aa3b, v150
	v_exp_f32_e32 v147, v147
	s_nop 0
	v_add_f32_e32 v147, 1.0, v147
	v_rcp_f32_e32 v147, v147
	s_nop 0
	v_mul_f32_e32 v147, v150, v147
	v_mul_f32_e32 v150, 0xbfb8aa3b, v154
	v_exp_f32_e32 v150, v150
	s_nop 0
	v_add_f32_e32 v150, 1.0, v150
	v_rcp_f32_e32 v150, v150
	s_nop 0
	v_mul_f32_e32 v150, v154, v150
	v_mul_f32_e32 v154, 0xbfb8aa3b, v151
	v_exp_f32_e32 v154, v154
	s_nop 0
	v_add_f32_e32 v154, 1.0, v154
	v_rcp_f32_e32 v154, v154
	s_nop 0
	v_mul_f32_e32 v151, v151, v154
	v_mul_f32_e32 v154, 0xbfb8aa3b, v155
	v_exp_f32_e32 v154, v154
	s_nop 0
	v_add_f32_e32 v154, 1.0, v154
	v_rcp_f32_e32 v154, v154
	s_nop 0
	v_mul_f32_e32 v154, v155, v154
	v_mul_f32_e32 v155, 0xbfb8aa3b, v148
	v_exp_f32_e32 v155, v155
	s_nop 0
	v_add_f32_e32 v155, 1.0, v155
	v_rcp_f32_e32 v155, v155
	s_nop 0
	v_mul_f32_e32 v155, v148, v155
	v_mul_f32_e32 v148, 0xbfb8aa3b, v152
	v_exp_f32_e32 v148, v148
	s_nop 0
	v_add_f32_e32 v148, 1.0, v148
	v_rcp_f32_e32 v148, v148
	s_nop 0
	v_mul_f32_e32 v152, v152, v148
	v_mul_f32_e32 v148, 0xbfb8aa3b, v149
	v_exp_f32_e32 v148, v148
	s_nop 0
	v_add_f32_e32 v148, 1.0, v148
	v_rcp_f32_e32 v148, v148
	s_nop 0
	v_mul_f32_e32 v149, v149, v148
	v_mul_f32_e32 v148, 0xbfb8aa3b, v153
	v_exp_f32_e32 v148, v148
	s_nop 0
	v_add_f32_e32 v148, 1.0, v148
	v_rcp_f32_e32 v148, v148
	s_nop 0
	v_mul_f32_e32 v153, v153, v148
	v_cvt_pk_bf16_f32 v148, v147, v151
	v_cvt_pk_bf16_f32 v149, v155, v149
	v_cvt_pk_bf16_f32 v150, v150, v154
	v_cvt_pk_bf16_f32 v151, v152, v153
	global_store_dwordx4 v[144:145], v[148:151], off offset:256
	v_fmamk_f32 v144, v194, 0x3a000000, v200
	v_cmp_gt_f32_e32 vcc, s91, v144
	v_mul_f32_e32 v145, 0x4b800000, v144
	s_nop 0
	v_cndmask_b32_e32 v144, v144, v145, vcc
	v_rsq_f32_e32 v144, v144
	s_nop 0
	v_mul_f32_e32 v145, 0x45800000, v144
	v_cndmask_b32_e32 v144, v144, v145, vcc
	v_pk_mul_f32 v[154:155], v[116:117], v[144:145] op_sel_hi:[1,0]
	v_pk_mul_f32 v[148:149], v[122:123], v[144:145] op_sel_hi:[1,0]
	v_mul_f32_e32 v147, 0xbfb8aa3b, v154
	v_exp_f32_e32 v147, v147
	v_pk_mul_f32 v[150:151], v[120:121], v[144:145] op_sel_hi:[1,0]
	v_pk_mul_f32 v[152:153], v[118:119], v[144:145] op_sel_hi:[1,0]
	v_mul_f32_e32 v145, 0xbfb8aa3b, v150
	v_add_f32_e32 v147, 1.0, v147
	v_rcp_f32_e32 v147, v147
	v_exp_f32_e32 v145, v145
	v_mul_f32_e32 v147, v154, v147
	v_mul_f32_e32 v154, 0xbfb8aa3b, v148
	v_exp_f32_e32 v154, v154
	v_add_f32_e32 v145, 1.0, v145
	v_rcp_f32_e32 v145, v145
	v_add_f32_e32 v154, 1.0, v154
	v_rcp_f32_e32 v154, v154
	v_mul_f32_e32 v145, v150, v145
	v_mul_f32_e32 v150, 0xbfb8aa3b, v151
	v_exp_f32_e32 v150, v150
	v_mul_f32_e32 v154, v148, v154
	v_mul_f32_e32 v148, 0xbfb8aa3b, v152
	v_exp_f32_e32 v148, v148
	v_add_f32_e32 v150, 1.0, v150
	v_rcp_f32_e32 v150, v150
	v_add_f32_e32 v148, 1.0, v148
	v_rcp_f32_e32 v148, v148
	v_mul_f32_e32 v150, v151, v150
	v_mul_f32_e32 v151, 0xbfb8aa3b, v155
	v_exp_f32_e32 v151, v151
	v_mul_f32_e32 v152, v152, v148
	v_mul_f32_e32 v148, 0xbfb8aa3b, v149
	v_exp_f32_e32 v148, v148
	v_add_f32_e32 v151, 1.0, v151
	v_rcp_f32_e32 v151, v151
	v_add_f32_e32 v148, 1.0, v148
	v_rcp_f32_e32 v148, v148
	v_mul_f32_e32 v151, v155, v151
	v_mul_f32_e32 v149, v149, v148
	v_mul_f32_e32 v148, 0xbfb8aa3b, v153
	v_exp_f32_e32 v148, v148
	s_nop 0
	v_add_f32_e32 v148, 1.0, v148
	v_rcp_f32_e32 v148, v148
	s_nop 0
	v_mul_f32_e32 v153, v153, v148
	v_cvt_pk_bf16_f32 v148, v145, v150
	v_cvt_pk_bf16_f32 v149, v154, v149
	v_cvt_pk_bf16_f32 v150, v147, v151
	v_cvt_pk_bf16_f32 v151, v152, v153
	global_store_dwordx4 v[142:143], v[148:151], off
	v_pk_mul_f32 v[152:153], v[86:87], v[144:145] op_sel_hi:[1,0]
	s_nop 0
	v_pk_mul_f32 v[150:151], v[88:89], v[144:145] op_sel_hi:[1,0]
	v_pk_mul_f32 v[148:149], v[90:91], v[144:145] op_sel_hi:[1,0]
	v_mul_f32_e32 v147, 0xbfb8aa3b, v150
	v_exp_f32_e32 v147, v147
	v_pk_mul_f32 v[144:145], v[84:85], v[144:145] op_sel_hi:[1,0]
	v_add_f32_e32 v147, 1.0, v147
	v_rcp_f32_e32 v147, v147
	s_nop 0
	v_mul_f32_e32 v147, v150, v147
	v_mul_f32_e32 v150, 0xbfb8aa3b, v144
	v_exp_f32_e32 v150, v150
	s_nop 0
	v_add_f32_e32 v150, 1.0, v150
	v_rcp_f32_e32 v150, v150
	s_nop 0
	v_mul_f32_e32 v144, v144, v150
	v_mul_f32_e32 v150, 0xbfb8aa3b, v151
	v_exp_f32_e32 v150, v150
	s_nop 0
	v_add_f32_e32 v150, 1.0, v150
	v_rcp_f32_e32 v150, v150
	s_nop 0
	v_mul_f32_e32 v150, v151, v150
	v_mul_f32_e32 v151, 0xbfb8aa3b, v145
	v_exp_f32_e32 v151, v151
	s_nop 0
	v_add_f32_e32 v151, 1.0, v151
	v_rcp_f32_e32 v151, v151
	s_nop 0
	v_mul_f32_e32 v145, v145, v151
	v_mul_f32_e32 v151, 0xbfb8aa3b, v148
	v_exp_f32_e32 v151, v151
	s_nop 0
	v_add_f32_e32 v151, 1.0, v151
	v_rcp_f32_e32 v151, v151
	s_nop 0
	v_mul_f32_e32 v151, v148, v151
	v_mul_f32_e32 v148, 0xbfb8aa3b, v152
	v_exp_f32_e32 v148, v148
	s_nop 0
	v_add_f32_e32 v148, 1.0, v148
	v_rcp_f32_e32 v148, v148
	s_nop 0
	v_mul_f32_e32 v152, v152, v148
	v_mul_f32_e32 v148, 0xbfb8aa3b, v149
	v_exp_f32_e32 v148, v148
	s_nop 0
	v_add_f32_e32 v148, 1.0, v148
	v_rcp_f32_e32 v148, v148
	s_nop 0
	v_mul_f32_e32 v149, v149, v148
	v_mul_f32_e32 v148, 0xbfb8aa3b, v153
	v_exp_f32_e32 v148, v148
	s_nop 0
	v_add_f32_e32 v148, 1.0, v148
	v_rcp_f32_e32 v148, v148
	s_nop 0
	v_mul_f32_e32 v153, v153, v148
	v_cvt_pk_bf16_f32 v148, v147, v150
	v_cvt_pk_bf16_f32 v149, v151, v149
	v_cvt_pk_bf16_f32 v150, v144, v145
	v_cvt_pk_bf16_f32 v151, v152, v153
	global_store_dwordx4 v[142:143], v[148:151], off offset:256
	v_fmamk_f32 v142, v211, 0x3a000000, v200
	v_cmp_gt_f32_e32 vcc, s91, v142
	v_mul_f32_e32 v143, 0x4b800000, v142
	s_nop 0
	v_cndmask_b32_e32 v142, v142, v143, vcc
	v_rsq_f32_e32 v142, v142
	s_nop 0
	v_mul_f32_e32 v143, 0x45800000, v142
	v_cndmask_b32_e32 v148, v142, v143, vcc
	v_pk_mul_f32 v[144:145], v[112:113], v[148:149] op_sel_hi:[1,0]
	v_pk_mul_f32 v[152:153], v[108:109], v[148:149] op_sel_hi:[1,0]
	v_mul_f32_e32 v147, 0xbfb8aa3b, v144
	v_exp_f32_e32 v147, v147
	v_pk_mul_f32 v[142:143], v[114:115], v[148:149] op_sel_hi:[1,0]
	v_pk_mul_f32 v[150:151], v[110:111], v[148:149] op_sel_hi:[1,0]
	v_mul_f32_e32 v149, 0xbfb8aa3b, v145
	v_add_f32_e32 v147, 1.0, v147
	v_rcp_f32_e32 v147, v147
	v_exp_f32_e32 v149, v149
	v_mul_f32_e32 v144, v144, v147
	v_mul_f32_e32 v147, 0xbfb8aa3b, v152
	v_exp_f32_e32 v147, v147
	v_add_f32_e32 v149, 1.0, v149
	v_rcp_f32_e32 v149, v149
	v_add_f32_e32 v147, 1.0, v147
	v_rcp_f32_e32 v147, v147
	v_mul_f32_e32 v145, v145, v149
	v_mul_f32_e32 v149, 0xbfb8aa3b, v153
	v_exp_f32_e32 v149, v149
	v_mul_f32_e32 v147, v152, v147
	v_mul_f32_e32 v152, 0xbfb8aa3b, v142
	v_exp_f32_e32 v152, v152
	v_add_f32_e32 v149, 1.0, v149
	v_rcp_f32_e32 v149, v149
	v_add_f32_e32 v152, 1.0, v152
	v_rcp_f32_e32 v152, v152
	v_mul_f32_e32 v149, v153, v149
	v_mul_f32_e32 v152, v142, v152
	v_mul_f32_e32 v142, 0xbfb8aa3b, v150
	v_exp_f32_e32 v142, v142
	s_nop 0
	v_add_f32_e32 v142, 1.0, v142
	v_rcp_f32_e32 v142, v142
	s_nop 0
	v_mul_f32_e32 v150, v150, v142
	v_mul_f32_e32 v142, 0xbfb8aa3b, v143
	v_exp_f32_e32 v142, v142
	s_nop 0
	v_add_f32_e32 v142, 1.0, v142
	v_rcp_f32_e32 v142, v142
	s_nop 0
	v_mul_f32_e32 v143, v143, v142
	v_mul_f32_e32 v142, 0xbfb8aa3b, v151
	v_exp_f32_e32 v142, v142
	s_nop 0
	v_add_f32_e32 v142, 1.0, v142
	v_rcp_f32_e32 v142, v142
	s_nop 0
	v_mul_f32_e32 v151, v151, v142
	v_cvt_pk_bf16_f32 v142, v144, v145
	v_cvt_pk_bf16_f32 v143, v152, v143
	v_cvt_pk_bf16_f32 v144, v147, v149
	v_cvt_pk_bf16_f32 v145, v150, v151
	global_store_dwordx4 v[140:141], v[142:145], off
	v_pk_mul_f32 v[150:151], v[78:79], v[148:149] op_sel_hi:[1,0]
	s_nop 0
	v_pk_mul_f32 v[144:145], v[80:81], v[148:149] op_sel_hi:[1,0]
	v_pk_mul_f32 v[142:143], v[82:83], v[148:149] op_sel_hi:[1,0]
	v_mul_f32_e32 v147, 0xbfb8aa3b, v144
	v_exp_f32_e32 v147, v147
	v_pk_mul_f32 v[148:149], v[76:77], v[148:149] op_sel_hi:[1,0]
	v_add_f32_e32 v147, 1.0, v147
	v_rcp_f32_e32 v147, v147
	s_nop 0
	v_mul_f32_e32 v144, v144, v147
	v_mul_f32_e32 v147, 0xbfb8aa3b, v148
	v_exp_f32_e32 v147, v147
	s_nop 0
	v_add_f32_e32 v147, 1.0, v147
	v_rcp_f32_e32 v147, v147
	s_nop 0
	v_mul_f32_e32 v147, v148, v147
	v_mul_f32_e32 v148, 0xbfb8aa3b, v145
	v_exp_f32_e32 v148, v148
	s_nop 0
	v_add_f32_e32 v148, 1.0, v148
	v_rcp_f32_e32 v148, v148
	s_nop 0
	v_mul_f32_e32 v145, v145, v148
	v_mul_f32_e32 v148, 0xbfb8aa3b, v149
	v_exp_f32_e32 v148, v148
	s_nop 0
	v_add_f32_e32 v148, 1.0, v148
	v_rcp_f32_e32 v148, v148
	s_nop 0
	v_mul_f32_e32 v148, v149, v148
	v_mul_f32_e32 v149, 0xbfb8aa3b, v142
	v_exp_f32_e32 v149, v149
	s_nop 0
	v_add_f32_e32 v149, 1.0, v149
	v_rcp_f32_e32 v149, v149
	s_nop 0
	v_mul_f32_e32 v149, v142, v149
	v_mul_f32_e32 v142, 0xbfb8aa3b, v150
	v_exp_f32_e32 v142, v142
	s_nop 0
	v_add_f32_e32 v142, 1.0, v142
	v_rcp_f32_e32 v142, v142
	s_nop 0
	v_mul_f32_e32 v150, v150, v142
	v_mul_f32_e32 v142, 0xbfb8aa3b, v143
	v_exp_f32_e32 v142, v142
	s_nop 0
	v_add_f32_e32 v142, 1.0, v142
	v_rcp_f32_e32 v142, v142
	s_nop 0
	v_mul_f32_e32 v143, v143, v142
	v_mul_f32_e32 v142, 0xbfb8aa3b, v151
	v_exp_f32_e32 v142, v142
	s_nop 0
	v_add_f32_e32 v142, 1.0, v142
	v_rcp_f32_e32 v142, v142
	s_nop 0
	v_mul_f32_e32 v151, v151, v142
	v_cvt_pk_bf16_f32 v142, v144, v145
	v_cvt_pk_bf16_f32 v143, v149, v143
	v_cvt_pk_bf16_f32 v144, v147, v148
	v_cvt_pk_bf16_f32 v145, v150, v151
	global_store_dwordx4 v[140:141], v[142:145], off offset:256
	v_fmamk_f32 v140, v210, 0x3a000000, v200
	v_cmp_gt_f32_e32 vcc, s91, v140
	v_mul_f32_e32 v141, 0x4b800000, v140
	s_nop 0
	v_cndmask_b32_e32 v140, v140, v141, vcc
	v_rsq_f32_e32 v140, v140
	s_nop 0
	v_mul_f32_e32 v141, 0x45800000, v140
	v_cndmask_b32_e32 v144, v140, v141, vcc
	v_pk_mul_f32 v[142:143], v[104:105], v[144:145] op_sel_hi:[1,0]
	v_pk_mul_f32 v[140:141], v[106:107], v[144:145] op_sel_hi:[1,0]
	v_pk_mul_f32 v[148:149], v[102:103], v[144:145] op_sel_hi:[1,0]
	v_pk_mul_f32 v[150:151], v[100:101], v[144:145] op_sel_hi:[1,0]
	v_mul_f32_e32 v145, 0xbfb8aa3b, v142
	v_exp_f32_e32 v145, v145
	v_mul_f32_e32 v147, 0xbfb8aa3b, v143
	v_exp_f32_e32 v147, v147
	v_add_f32_e32 v145, 1.0, v145
	v_rcp_f32_e32 v145, v145
	v_add_f32_e32 v147, 1.0, v147
	v_rcp_f32_e32 v147, v147
	v_mul_f32_e32 v142, v142, v145
	v_mul_f32_e32 v145, 0xbfb8aa3b, v150
	v_exp_f32_e32 v145, v145
	v_mul_f32_e32 v143, v143, v147
	v_mul_f32_e32 v147, 0xbfb8aa3b, v151
	v_exp_f32_e32 v147, v147
	v_add_f32_e32 v145, 1.0, v145
	v_rcp_f32_e32 v145, v145
	v_add_f32_e32 v147, 1.0, v147
	v_rcp_f32_e32 v147, v147
	v_mul_f32_e32 v145, v150, v145
	v_mul_f32_e32 v150, 0xbfb8aa3b, v140
	v_exp_f32_e32 v150, v150
	v_mul_f32_e32 v147, v151, v147
	v_add_f32_e32 v150, 1.0, v150
	v_rcp_f32_e32 v150, v150
	s_nop 0
	v_mul_f32_e32 v150, v140, v150
	v_mul_f32_e32 v140, 0xbfb8aa3b, v148
	v_exp_f32_e32 v140, v140
	s_nop 0
	v_add_f32_e32 v140, 1.0, v140
	v_rcp_f32_e32 v140, v140
	s_nop 0
	v_mul_f32_e32 v148, v148, v140
	v_mul_f32_e32 v140, 0xbfb8aa3b, v141
	v_exp_f32_e32 v140, v140
	s_nop 0
	v_add_f32_e32 v140, 1.0, v140
	v_rcp_f32_e32 v140, v140
	s_nop 0
	v_mul_f32_e32 v141, v141, v140
	v_mul_f32_e32 v140, 0xbfb8aa3b, v149
	v_exp_f32_e32 v140, v140
	s_nop 0
	v_add_f32_e32 v140, 1.0, v140
	v_rcp_f32_e32 v140, v140
	s_nop 0
	v_mul_f32_e32 v149, v149, v140
	v_cvt_pk_bf16_f32 v140, v142, v143
	v_cvt_pk_bf16_f32 v141, v150, v141
	v_cvt_pk_bf16_f32 v142, v145, v147
	v_cvt_pk_bf16_f32 v143, v148, v149
	global_store_dwordx4 v[138:139], v[140:143], off
	v_pk_mul_f32 v[148:149], v[70:71], v[144:145] op_sel_hi:[1,0]
	s_nop 0
	v_pk_mul_f32 v[142:143], v[72:73], v[144:145] op_sel_hi:[1,0]
	v_pk_mul_f32 v[140:141], v[74:75], v[144:145] op_sel_hi:[1,0]
	v_mul_f32_e32 v147, 0xbfb8aa3b, v142
	v_exp_f32_e32 v147, v147
	v_pk_mul_f32 v[144:145], v[68:69], v[144:145] op_sel_hi:[1,0]
	v_add_f32_e32 v147, 1.0, v147
	v_rcp_f32_e32 v147, v147
	s_nop 0
	v_mul_f32_e32 v142, v142, v147
	v_mul_f32_e32 v147, 0xbfb8aa3b, v144
	v_exp_f32_e32 v147, v147
	s_nop 0
	v_add_f32_e32 v147, 1.0, v147
	v_rcp_f32_e32 v147, v147
	s_nop 0
	v_mul_f32_e32 v144, v144, v147
	v_mul_f32_e32 v147, 0xbfb8aa3b, v143
	v_exp_f32_e32 v147, v147
	s_nop 0
	v_add_f32_e32 v147, 1.0, v147
	v_rcp_f32_e32 v147, v147
	s_nop 0
	v_mul_f32_e32 v143, v143, v147
	v_mul_f32_e32 v147, 0xbfb8aa3b, v145
	v_exp_f32_e32 v147, v147
	s_nop 0
	v_add_f32_e32 v147, 1.0, v147
	v_rcp_f32_e32 v147, v147
	s_nop 0
	v_mul_f32_e32 v145, v145, v147
	v_mul_f32_e32 v147, 0xbfb8aa3b, v140
	v_exp_f32_e32 v147, v147
	s_nop 0
	v_add_f32_e32 v147, 1.0, v147
	v_rcp_f32_e32 v147, v147
	s_nop 0
	v_mul_f32_e32 v147, v140, v147
	v_mul_f32_e32 v140, 0xbfb8aa3b, v148
	v_exp_f32_e32 v140, v140
	s_nop 0
	v_add_f32_e32 v140, 1.0, v140
	v_rcp_f32_e32 v140, v140
	s_nop 0
	v_mul_f32_e32 v148, v148, v140
	v_mul_f32_e32 v140, 0xbfb8aa3b, v141
	v_exp_f32_e32 v140, v140
	s_nop 0
	v_add_f32_e32 v140, 1.0, v140
	v_rcp_f32_e32 v140, v140
	s_nop 0
	v_mul_f32_e32 v141, v141, v140
	v_mul_f32_e32 v140, 0xbfb8aa3b, v149
	v_exp_f32_e32 v140, v140
	s_nop 0
	v_add_f32_e32 v140, 1.0, v140
	v_rcp_f32_e32 v140, v140
	s_nop 0
	v_mul_f32_e32 v149, v149, v140
	v_cvt_pk_bf16_f32 v140, v142, v143
	v_cvt_pk_bf16_f32 v141, v147, v141
	v_cvt_pk_bf16_f32 v142, v144, v145
	v_cvt_pk_bf16_f32 v143, v148, v149
	global_store_dwordx4 v[138:139], v[140:143], off offset:256
	v_fmamk_f32 v138, v209, 0x3a000000, v200
	v_cmp_gt_f32_e32 vcc, s91, v138
	v_mul_f32_e32 v139, 0x4b800000, v138
	s_nop 0
	v_cndmask_b32_e32 v138, v138, v139, vcc
	v_rsq_f32_e32 v138, v138
	s_nop 0
	v_mul_f32_e32 v139, 0x45800000, v138
	v_cndmask_b32_e32 v144, v138, v139, vcc
	v_pk_mul_f32 v[142:143], v[64:65], v[144:145] op_sel_hi:[1,0]
	v_pk_mul_f32 v[140:141], v[66:67], v[144:145] op_sel_hi:[1,0]
	v_pk_mul_f32 v[148:149], v[62:63], v[144:145] op_sel_hi:[1,0]
	v_pk_mul_f32 v[150:151], v[60:61], v[144:145] op_sel_hi:[1,0]
	v_mul_f32_e32 v145, 0xbfb8aa3b, v142
	v_exp_f32_e32 v145, v145
	v_mul_f32_e32 v147, 0xbfb8aa3b, v143
	v_exp_f32_e32 v147, v147
	v_lshlrev_b64 v[138:139], 12, v[188:189]
	v_add_f32_e32 v145, 1.0, v145
	v_rcp_f32_e32 v145, v145
	v_add_f32_e32 v147, 1.0, v147
	v_rcp_f32_e32 v147, v147
	v_lshl_add_u64 v[138:139], v[136:137], 0, v[138:139]
	v_mul_f32_e32 v142, v142, v145
	v_mul_f32_e32 v145, 0xbfb8aa3b, v150
	v_exp_f32_e32 v145, v145
	v_mul_f32_e32 v143, v143, v147
	v_mul_f32_e32 v147, 0xbfb8aa3b, v151
	v_exp_f32_e32 v147, v147
	v_add_f32_e32 v145, 1.0, v145
	v_rcp_f32_e32 v145, v145
	v_lshl_add_u64 v[136:137], v[134:135], 0, s[0:1]
	v_add_f32_e32 v147, 1.0, v147
	v_rcp_f32_e32 v147, v147
	v_mul_f32_e32 v145, v150, v145
	v_mul_f32_e32 v150, 0xbfb8aa3b, v140
	v_exp_f32_e32 v150, v150
	v_mul_f32_e32 v147, v151, v147
	s_mov_b32 s0, 0x90000
	v_add_f32_e32 v150, 1.0, v150
	v_rcp_f32_e32 v150, v150
	s_nop 0
	v_mul_f32_e32 v150, v140, v150
	v_mul_f32_e32 v140, 0xbfb8aa3b, v148
	v_exp_f32_e32 v140, v140
	s_nop 0
	v_add_f32_e32 v140, 1.0, v140
	v_rcp_f32_e32 v140, v140
	s_nop 0
	v_mul_f32_e32 v148, v148, v140
	v_mul_f32_e32 v140, 0xbfb8aa3b, v141
	v_exp_f32_e32 v140, v140
	s_nop 0
	v_add_f32_e32 v140, 1.0, v140
	v_rcp_f32_e32 v140, v140
	s_nop 0
	v_mul_f32_e32 v141, v141, v140
	v_mul_f32_e32 v140, 0xbfb8aa3b, v149
	v_exp_f32_e32 v140, v140
	s_nop 0
	v_add_f32_e32 v140, 1.0, v140
	v_rcp_f32_e32 v140, v140
	s_nop 0
	v_mul_f32_e32 v149, v149, v140
	v_cvt_pk_bf16_f32 v140, v142, v143
	v_cvt_pk_bf16_f32 v141, v150, v141
	v_cvt_pk_bf16_f32 v142, v145, v147
	v_cvt_pk_bf16_f32 v143, v148, v149
	global_store_dwordx4 v[138:139], v[140:143], off
	v_pk_mul_f32 v[148:149], v[30:31], v[144:145] op_sel_hi:[1,0]
	s_nop 0
	v_pk_mul_f32 v[142:143], v[32:33], v[144:145] op_sel_hi:[1,0]
	v_pk_mul_f32 v[140:141], v[34:35], v[144:145] op_sel_hi:[1,0]
	v_mul_f32_e32 v147, 0xbfb8aa3b, v142
	v_exp_f32_e32 v147, v147
	v_pk_mul_f32 v[144:145], v[28:29], v[144:145] op_sel_hi:[1,0]
	v_add_f32_e32 v147, 1.0, v147
	v_rcp_f32_e32 v147, v147
	s_nop 0
	v_mul_f32_e32 v142, v142, v147
	v_mul_f32_e32 v147, 0xbfb8aa3b, v144
	v_exp_f32_e32 v147, v147
	s_nop 0
	v_add_f32_e32 v147, 1.0, v147
	v_rcp_f32_e32 v147, v147
	s_nop 0
	v_mul_f32_e32 v144, v144, v147
	v_mul_f32_e32 v147, 0xbfb8aa3b, v143
	v_exp_f32_e32 v147, v147
	s_nop 0
	v_add_f32_e32 v147, 1.0, v147
	v_rcp_f32_e32 v147, v147
	s_nop 0
	v_mul_f32_e32 v143, v143, v147
	v_mul_f32_e32 v147, 0xbfb8aa3b, v145
	v_exp_f32_e32 v147, v147
	s_nop 0
	v_add_f32_e32 v147, 1.0, v147
	v_rcp_f32_e32 v147, v147
	s_nop 0
	v_mul_f32_e32 v145, v145, v147
	v_mul_f32_e32 v147, 0xbfb8aa3b, v140
	v_exp_f32_e32 v147, v147
	s_nop 0
	v_add_f32_e32 v147, 1.0, v147
	v_rcp_f32_e32 v147, v147
	s_nop 0
	v_mul_f32_e32 v147, v140, v147
	v_mul_f32_e32 v140, 0xbfb8aa3b, v148
	v_exp_f32_e32 v140, v140
	s_nop 0
	v_add_f32_e32 v140, 1.0, v140
	v_rcp_f32_e32 v140, v140
	s_nop 0
	v_mul_f32_e32 v148, v148, v140
	v_mul_f32_e32 v140, 0xbfb8aa3b, v141
	v_exp_f32_e32 v140, v140
	s_nop 0
	v_add_f32_e32 v140, 1.0, v140
	v_rcp_f32_e32 v140, v140
	s_nop 0
	v_mul_f32_e32 v141, v141, v140
	v_mul_f32_e32 v140, 0xbfb8aa3b, v149
	v_exp_f32_e32 v140, v140
	s_nop 0
	v_add_f32_e32 v140, 1.0, v140
	v_rcp_f32_e32 v140, v140
	s_nop 0
	v_mul_f32_e32 v149, v149, v140
	v_cvt_pk_bf16_f32 v140, v142, v143
	v_cvt_pk_bf16_f32 v141, v147, v141
	v_cvt_pk_bf16_f32 v142, v144, v145
	v_cvt_pk_bf16_f32 v143, v148, v149
	global_store_dwordx4 v[138:139], v[140:143], off offset:256
	v_fmamk_f32 v138, v208, 0x3a000000, v200
	v_cmp_gt_f32_e32 vcc, s91, v138
	v_mul_f32_e32 v139, 0x4b800000, v138
	s_nop 0
	v_cndmask_b32_e32 v138, v138, v139, vcc
	v_rsq_f32_e32 v138, v138
	s_nop 0
	v_mul_f32_e32 v139, 0x45800000, v138
	v_cndmask_b32_e32 v142, v138, v139, vcc
	v_pk_mul_f32 v[140:141], v[56:57], v[142:143] op_sel_hi:[1,0]
	v_pk_mul_f32 v[138:139], v[58:59], v[142:143] op_sel_hi:[1,0]
	v_pk_mul_f32 v[144:145], v[54:55], v[142:143] op_sel_hi:[1,0]
	v_pk_mul_f32 v[148:149], v[52:53], v[142:143] op_sel_hi:[1,0]
	v_mul_f32_e32 v143, 0xbfb8aa3b, v140
	v_exp_f32_e32 v143, v143
	v_mul_f32_e32 v147, 0xbfb8aa3b, v141
	v_exp_f32_e32 v147, v147
	v_add_f32_e32 v143, 1.0, v143
	v_rcp_f32_e32 v143, v143
	v_add_f32_e32 v147, 1.0, v147
	v_rcp_f32_e32 v147, v147
	v_mul_f32_e32 v140, v140, v143
	v_mul_f32_e32 v143, 0xbfb8aa3b, v148
	v_exp_f32_e32 v143, v143
	v_mul_f32_e32 v141, v141, v147
	v_mul_f32_e32 v147, 0xbfb8aa3b, v149
	v_exp_f32_e32 v147, v147
	v_add_f32_e32 v143, 1.0, v143
	v_rcp_f32_e32 v143, v143
	v_add_f32_e32 v147, 1.0, v147
	v_rcp_f32_e32 v147, v147
	v_mul_f32_e32 v143, v148, v143
	v_mul_f32_e32 v148, 0xbfb8aa3b, v138
	v_exp_f32_e32 v148, v148
	v_mul_f32_e32 v147, v149, v147
	v_add_f32_e32 v148, 1.0, v148
	v_rcp_f32_e32 v148, v148
	s_nop 0
	v_mul_f32_e32 v148, v138, v148
	v_mul_f32_e32 v138, 0xbfb8aa3b, v144
	v_exp_f32_e32 v138, v138
	s_nop 0
	v_add_f32_e32 v138, 1.0, v138
	v_rcp_f32_e32 v138, v138
	s_nop 0
	v_mul_f32_e32 v144, v144, v138
	v_mul_f32_e32 v138, 0xbfb8aa3b, v139
	v_exp_f32_e32 v138, v138
	s_nop 0
	v_add_f32_e32 v138, 1.0, v138
	v_rcp_f32_e32 v138, v138
	s_nop 0
	v_mul_f32_e32 v139, v139, v138
	v_mul_f32_e32 v138, 0xbfb8aa3b, v145
	v_exp_f32_e32 v138, v138
	s_nop 0
	v_add_f32_e32 v138, 1.0, v138
	v_rcp_f32_e32 v138, v138
	s_nop 0
	v_mul_f32_e32 v145, v145, v138
	v_cvt_pk_bf16_f32 v138, v140, v141
	v_cvt_pk_bf16_f32 v139, v148, v139
	v_cvt_pk_bf16_f32 v140, v143, v147
	v_cvt_pk_bf16_f32 v141, v144, v145
	v_add_co_u32_e32 v144, vcc, s0, v134
	s_mov_b64 s[0:1], 0xa0000
	s_nop 0
	v_addc_co_u32_e32 v145, vcc, 0, v135, vcc
	global_store_dwordx4 v[144:145], v[138:141], off
	v_pk_mul_f32 v[144:145], v[22:23], v[142:143] op_sel_hi:[1,0]
	s_nop 0
	v_pk_mul_f32 v[140:141], v[24:25], v[142:143] op_sel_hi:[1,0]
	v_pk_mul_f32 v[138:139], v[26:27], v[142:143] op_sel_hi:[1,0]
	v_mul_f32_e32 v147, 0xbfb8aa3b, v140
	v_exp_f32_e32 v147, v147
	v_pk_mul_f32 v[142:143], v[20:21], v[142:143] op_sel_hi:[1,0]
	v_add_f32_e32 v147, 1.0, v147
	v_rcp_f32_e32 v147, v147
	s_nop 0
	v_mul_f32_e32 v140, v140, v147
	v_mul_f32_e32 v147, 0xbfb8aa3b, v142
	v_exp_f32_e32 v147, v147
	s_nop 0
	v_add_f32_e32 v147, 1.0, v147
	v_rcp_f32_e32 v147, v147
	s_nop 0
	v_mul_f32_e32 v142, v142, v147
	v_mul_f32_e32 v147, 0xbfb8aa3b, v141
	v_exp_f32_e32 v147, v147
	s_nop 0
	v_add_f32_e32 v147, 1.0, v147
	v_rcp_f32_e32 v147, v147
	s_nop 0
	v_mul_f32_e32 v141, v141, v147
	v_mul_f32_e32 v147, 0xbfb8aa3b, v143
	v_exp_f32_e32 v147, v147
	s_nop 0
	v_add_f32_e32 v147, 1.0, v147
	v_rcp_f32_e32 v147, v147
	s_nop 0
	v_mul_f32_e32 v143, v143, v147
	v_mul_f32_e32 v147, 0xbfb8aa3b, v138
	v_exp_f32_e32 v147, v147
	s_nop 0
	v_add_f32_e32 v147, 1.0, v147
	v_rcp_f32_e32 v147, v147
	s_nop 0
	v_mul_f32_e32 v147, v138, v147
	v_mul_f32_e32 v138, 0xbfb8aa3b, v144
	v_exp_f32_e32 v138, v138
	s_nop 0
	v_add_f32_e32 v138, 1.0, v138
	v_rcp_f32_e32 v138, v138
	s_nop 0
	v_mul_f32_e32 v144, v144, v138
	v_mul_f32_e32 v138, 0xbfb8aa3b, v139
	v_exp_f32_e32 v138, v138
	s_nop 0
	v_add_f32_e32 v138, 1.0, v138
	v_rcp_f32_e32 v138, v138
	s_nop 0
	v_mul_f32_e32 v139, v139, v138
	v_mul_f32_e32 v138, 0xbfb8aa3b, v145
	v_exp_f32_e32 v138, v138
	s_nop 0
	v_add_f32_e32 v138, 1.0, v138
	v_rcp_f32_e32 v138, v138
	s_nop 0
	v_mul_f32_e32 v145, v145, v138
	v_cvt_pk_bf16_f32 v138, v140, v141
	v_cvt_pk_bf16_f32 v139, v147, v139
	v_cvt_pk_bf16_f32 v140, v142, v143
	v_cvt_pk_bf16_f32 v141, v144, v145
	global_store_dwordx4 v[136:137], v[138:141], off offset:256
	v_fmamk_f32 v136, v207, 0x3a000000, v200
	v_cmp_gt_f32_e32 vcc, s91, v136
	v_mul_f32_e32 v137, 0x4b800000, v136
	s_nop 0
	v_cndmask_b32_e32 v136, v136, v137, vcc
	v_rsq_f32_e32 v136, v136
	s_nop 0
	v_mul_f32_e32 v137, 0x45800000, v136
	v_cndmask_b32_e32 v142, v136, v137, vcc
	v_pk_mul_f32 v[140:141], v[48:49], v[142:143] op_sel_hi:[1,0]
	v_pk_mul_f32 v[138:139], v[50:51], v[142:143] op_sel_hi:[1,0]
	v_pk_mul_f32 v[144:145], v[46:47], v[142:143] op_sel_hi:[1,0]
	v_pk_mul_f32 v[148:149], v[44:45], v[142:143] op_sel_hi:[1,0]
	v_mul_f32_e32 v143, 0xbfb8aa3b, v140
	v_exp_f32_e32 v143, v143
	v_mul_f32_e32 v147, 0xbfb8aa3b, v141
	v_exp_f32_e32 v147, v147
	v_lshl_add_u64 v[136:137], v[134:135], 0, s[0:1]
	v_add_f32_e32 v143, 1.0, v143
	v_rcp_f32_e32 v143, v143
	v_add_f32_e32 v147, 1.0, v147
	v_rcp_f32_e32 v147, v147
	s_mov_b32 s0, 0xa0000
	v_mul_f32_e32 v140, v140, v143
	v_mul_f32_e32 v143, 0xbfb8aa3b, v148
	v_exp_f32_e32 v143, v143
	v_mul_f32_e32 v141, v141, v147
	v_mul_f32_e32 v147, 0xbfb8aa3b, v149
	v_exp_f32_e32 v147, v147
	v_add_f32_e32 v143, 1.0, v143
	v_rcp_f32_e32 v143, v143
	v_add_f32_e32 v147, 1.0, v147
	v_rcp_f32_e32 v147, v147
	v_mul_f32_e32 v143, v148, v143
	v_mul_f32_e32 v148, 0xbfb8aa3b, v138
	v_exp_f32_e32 v148, v148
	v_mul_f32_e32 v147, v149, v147
	v_add_f32_e32 v148, 1.0, v148
	v_rcp_f32_e32 v148, v148
	s_nop 0
	v_mul_f32_e32 v148, v138, v148
	v_mul_f32_e32 v138, 0xbfb8aa3b, v144
	v_exp_f32_e32 v138, v138
	s_nop 0
	v_add_f32_e32 v138, 1.0, v138
	v_rcp_f32_e32 v138, v138
	s_nop 0
	v_mul_f32_e32 v144, v144, v138
	v_mul_f32_e32 v138, 0xbfb8aa3b, v139
	v_exp_f32_e32 v138, v138
	s_nop 0
	v_add_f32_e32 v138, 1.0, v138
	v_rcp_f32_e32 v138, v138
	s_nop 0
	v_mul_f32_e32 v139, v139, v138
	v_mul_f32_e32 v138, 0xbfb8aa3b, v145
	v_exp_f32_e32 v138, v138
	s_nop 0
	v_add_f32_e32 v138, 1.0, v138
	v_rcp_f32_e32 v138, v138
	s_nop 0
	v_mul_f32_e32 v145, v145, v138
	v_cvt_pk_bf16_f32 v138, v140, v141
	v_cvt_pk_bf16_f32 v139, v148, v139
	v_cvt_pk_bf16_f32 v140, v143, v147
	v_cvt_pk_bf16_f32 v141, v144, v145
	v_add_co_u32_e32 v144, vcc, s0, v134
	s_mov_b64 s[0:1], 0xb0000
	s_nop 0
	v_addc_co_u32_e32 v145, vcc, 0, v135, vcc
	global_store_dwordx4 v[144:145], v[138:141], off
	v_pk_mul_f32 v[144:145], v[14:15], v[142:143] op_sel_hi:[1,0]
	s_nop 0
	v_pk_mul_f32 v[140:141], v[16:17], v[142:143] op_sel_hi:[1,0]
	v_pk_mul_f32 v[138:139], v[18:19], v[142:143] op_sel_hi:[1,0]
	v_mul_f32_e32 v147, 0xbfb8aa3b, v140
	v_exp_f32_e32 v147, v147
	v_pk_mul_f32 v[142:143], v[12:13], v[142:143] op_sel_hi:[1,0]
	v_add_f32_e32 v147, 1.0, v147
	v_rcp_f32_e32 v147, v147
	s_nop 0
	v_mul_f32_e32 v140, v140, v147
	v_mul_f32_e32 v147, 0xbfb8aa3b, v142
	v_exp_f32_e32 v147, v147
	s_nop 0
	v_add_f32_e32 v147, 1.0, v147
	v_rcp_f32_e32 v147, v147
	s_nop 0
	v_mul_f32_e32 v142, v142, v147
	v_mul_f32_e32 v147, 0xbfb8aa3b, v141
	v_exp_f32_e32 v147, v147
	s_nop 0
	v_add_f32_e32 v147, 1.0, v147
	v_rcp_f32_e32 v147, v147
	s_nop 0
	v_mul_f32_e32 v141, v141, v147
	v_mul_f32_e32 v147, 0xbfb8aa3b, v143
	v_exp_f32_e32 v147, v147
	s_nop 0
	v_add_f32_e32 v147, 1.0, v147
	v_rcp_f32_e32 v147, v147
	s_nop 0
	v_mul_f32_e32 v143, v143, v147
	v_mul_f32_e32 v147, 0xbfb8aa3b, v138
	v_exp_f32_e32 v147, v147
	s_nop 0
	v_add_f32_e32 v147, 1.0, v147
	v_rcp_f32_e32 v147, v147
	s_nop 0
	v_mul_f32_e32 v147, v138, v147
	v_mul_f32_e32 v138, 0xbfb8aa3b, v144
	v_exp_f32_e32 v138, v138
	s_nop 0
	v_add_f32_e32 v138, 1.0, v138
	v_rcp_f32_e32 v138, v138
	s_nop 0
	v_mul_f32_e32 v144, v144, v138
	v_mul_f32_e32 v138, 0xbfb8aa3b, v139
	v_exp_f32_e32 v138, v138
	s_nop 0
	v_add_f32_e32 v138, 1.0, v138
	v_rcp_f32_e32 v138, v138
	s_nop 0
	v_mul_f32_e32 v139, v139, v138
	v_mul_f32_e32 v138, 0xbfb8aa3b, v145
	v_exp_f32_e32 v138, v138
	s_nop 0
	v_add_f32_e32 v138, 1.0, v138
	v_rcp_f32_e32 v138, v138
	s_nop 0
	v_mul_f32_e32 v145, v145, v138
	v_cvt_pk_bf16_f32 v138, v140, v141
	v_cvt_pk_bf16_f32 v139, v147, v139
	v_cvt_pk_bf16_f32 v140, v142, v143
	v_cvt_pk_bf16_f32 v141, v144, v145
	global_store_dwordx4 v[136:137], v[138:141], off offset:256
	v_fmamk_f32 v136, v206, 0x3a000000, v200
	v_cmp_gt_f32_e32 vcc, s91, v136
	v_mul_f32_e32 v137, 0x4b800000, v136
	s_nop 0
	v_cndmask_b32_e32 v136, v136, v137, vcc
	v_rsq_f32_e32 v136, v136
	s_nop 0
	v_mul_f32_e32 v137, 0x45800000, v136
	v_cndmask_b32_e32 v142, v136, v137, vcc
	v_pk_mul_f32 v[140:141], v[40:41], v[142:143] op_sel_hi:[1,0]
	v_pk_mul_f32 v[138:139], v[42:43], v[142:143] op_sel_hi:[1,0]
	v_pk_mul_f32 v[144:145], v[38:39], v[142:143] op_sel_hi:[1,0]
	v_pk_mul_f32 v[148:149], v[36:37], v[142:143] op_sel_hi:[1,0]
	v_mul_f32_e32 v143, 0xbfb8aa3b, v140
	v_exp_f32_e32 v143, v143
	v_mul_f32_e32 v147, 0xbfb8aa3b, v141
	v_exp_f32_e32 v147, v147
	v_lshl_add_u64 v[136:137], v[134:135], 0, s[0:1]
	v_add_f32_e32 v143, 1.0, v143
	v_rcp_f32_e32 v143, v143
	v_add_f32_e32 v147, 1.0, v147
	v_rcp_f32_e32 v147, v147
	s_mov_b32 s0, 0xb0000
	v_mul_f32_e32 v140, v140, v143
	v_mul_f32_e32 v143, 0xbfb8aa3b, v148
	v_exp_f32_e32 v143, v143
	v_mul_f32_e32 v141, v141, v147
	v_mul_f32_e32 v147, 0xbfb8aa3b, v149
	v_exp_f32_e32 v147, v147
	v_add_f32_e32 v143, 1.0, v143
	v_rcp_f32_e32 v143, v143
	v_add_co_u32_e32 v134, vcc, s0, v134
	v_add_f32_e32 v147, 1.0, v147
	v_mul_f32_e32 v143, v148, v143
	v_mul_f32_e32 v148, 0xbfb8aa3b, v138
	v_exp_f32_e32 v148, v148
	v_rcp_f32_e32 v147, v147
	v_addc_co_u32_e32 v135, vcc, 0, v135, vcc
	v_add_f32_e32 v148, 1.0, v148
	v_rcp_f32_e32 v148, v148
	v_mul_f32_e32 v147, v149, v147
	s_mov_b64 s[0:1], 0
	v_mul_f32_e32 v148, v138, v148
	v_mul_f32_e32 v138, 0xbfb8aa3b, v144
	v_exp_f32_e32 v138, v138
	s_nop 0
	v_add_f32_e32 v138, 1.0, v138
	v_rcp_f32_e32 v138, v138
	s_nop 0
	v_mul_f32_e32 v144, v144, v138
	v_mul_f32_e32 v138, 0xbfb8aa3b, v139
	v_exp_f32_e32 v138, v138
	s_nop 0
	v_add_f32_e32 v138, 1.0, v138
	v_rcp_f32_e32 v138, v138
	s_nop 0
	v_mul_f32_e32 v139, v139, v138
	v_mul_f32_e32 v138, 0xbfb8aa3b, v145
	v_exp_f32_e32 v138, v138
	s_nop 0
	v_add_f32_e32 v138, 1.0, v138
	v_rcp_f32_e32 v138, v138
	s_nop 0
	v_mul_f32_e32 v145, v145, v138
	v_cvt_pk_bf16_f32 v138, v140, v141
	v_cvt_pk_bf16_f32 v139, v148, v139
	v_cvt_pk_bf16_f32 v140, v143, v147
	v_cvt_pk_bf16_f32 v141, v144, v145
	global_store_dwordx4 v[134:135], v[138:141], off
	v_pk_mul_f32 v[134:135], v[10:11], v[142:143] op_sel_hi:[1,0]
	s_nop 0
	v_pk_mul_f32 v[138:139], v[8:9], v[142:143] op_sel_hi:[1,0]
	v_pk_mul_f32 v[140:141], v[6:7], v[142:143] op_sel_hi:[1,0]
	v_mul_f32_e32 v144, 0xbfb8aa3b, v138
	v_exp_f32_e32 v144, v144
	v_pk_mul_f32 v[142:143], v[4:5], v[142:143] op_sel_hi:[1,0]
	v_add_f32_e32 v144, 1.0, v144
	v_rcp_f32_e32 v144, v144
	s_nop 0
	v_mul_f32_e32 v138, v138, v144
	v_mul_f32_e32 v144, 0xbfb8aa3b, v142
	v_exp_f32_e32 v144, v144
	s_nop 0
	v_add_f32_e32 v144, 1.0, v144
	v_rcp_f32_e32 v144, v144
	s_nop 0
	v_mul_f32_e32 v142, v142, v144
	v_mul_f32_e32 v144, 0xbfb8aa3b, v139
	v_exp_f32_e32 v144, v144
	s_nop 0
	v_add_f32_e32 v144, 1.0, v144
	v_rcp_f32_e32 v144, v144
	s_nop 0
	v_mul_f32_e32 v139, v139, v144
	v_mul_f32_e32 v144, 0xbfb8aa3b, v143
	v_exp_f32_e32 v144, v144
	v_cvt_pk_bf16_f32 v138, v138, v139
	s_nop 0
	v_add_f32_e32 v144, 1.0, v144
	v_rcp_f32_e32 v144, v144
	s_nop 0
	v_mul_f32_e32 v143, v143, v144
	v_mul_f32_e32 v144, 0xbfb8aa3b, v134
	v_exp_f32_e32 v144, v144
	s_nop 0
	v_add_f32_e32 v144, 1.0, v144
	v_rcp_f32_e32 v144, v144
	s_nop 0
	v_mul_f32_e32 v134, v134, v144
	v_mul_f32_e32 v144, 0xbfb8aa3b, v140
	v_exp_f32_e32 v144, v144
	s_nop 0
	v_add_f32_e32 v144, 1.0, v144
	v_rcp_f32_e32 v144, v144
	s_nop 0
	v_mul_f32_e32 v144, v140, v144
	v_mul_f32_e32 v140, 0xbfb8aa3b, v135
	v_exp_f32_e32 v140, v140
	s_nop 0
	v_add_f32_e32 v140, 1.0, v140
	v_rcp_f32_e32 v140, v140
	s_nop 0
	v_mul_f32_e32 v135, v135, v140
	v_mul_f32_e32 v140, 0xbfb8aa3b, v141
	v_exp_f32_e32 v140, v140
	v_cvt_pk_bf16_f32 v139, v134, v135
	s_nop 0
	v_add_f32_e32 v140, 1.0, v140
	v_rcp_f32_e32 v140, v140
	s_nop 0
	v_mul_f32_e32 v141, v141, v140
	v_cvt_pk_bf16_f32 v140, v142, v143
	v_cvt_pk_bf16_f32 v141, v144, v141
	global_store_dwordx4 v[136:137], v[138:141], off offset:256

	.amdhsa_kernel _Z4mega6Params
		.amdhsa_group_segment_fixed_size 0
		.amdhsa_private_segment_fixed_size 0
		.amdhsa_kernarg_size 384
		.amdhsa_user_sgpr_count 2
		.amdhsa_user_sgpr_dispatch_ptr 0
		.amdhsa_user_sgpr_queue_ptr 0
		.amdhsa_user_sgpr_kernarg_segment_ptr 1
		.amdhsa_user_sgpr_dispatch_id 0
		.amdhsa_user_sgpr_kernarg_preload_length 0
		.amdhsa_user_sgpr_kernarg_preload_offset 0
		.amdhsa_user_sgpr_private_segment_size 0
		.amdhsa_uses_dynamic_stack 0
		.amdhsa_enable_private_segment 0
		.amdhsa_system_sgpr_workgroup_id_x 1
		.amdhsa_system_sgpr_workgroup_id_y 0
		.amdhsa_system_sgpr_workgroup_id_z 0
		.amdhsa_system_sgpr_workgroup_info 0
		.amdhsa_system_vgpr_workitem_id 2
		.amdhsa_next_free_vgpr 252
		.amdhsa_next_free_sgpr 102
		.amdhsa_accum_offset 252
		.amdhsa_reserve_vcc 1
		.amdhsa_float_round_mode_32 0
		.amdhsa_float_round_mode_16_64 0
		.amdhsa_float_denorm_mode_32 3
		.amdhsa_float_denorm_mode_16_64 3
		.amdhsa_dx10_clamp 1
		.amdhsa_ieee_mode 1
		.amdhsa_fp16_overflow 0
		.amdhsa_tg_split 0
		.amdhsa_exception_fp_ieee_invalid_op 0
		.amdhsa_exception_fp_denorm_src 0
		.amdhsa_exception_fp_ieee_div_zero 0
		.amdhsa_exception_fp_ieee_overflow 0
		.amdhsa_exception_fp_ieee_underflow 0
		.amdhsa_exception_fp_ieee_inexact 0
		.amdhsa_exception_int_div_zero 0
	.end_amdhsa_kernel

amdhsa.kernels:
  - .agpr_count:     0
    .args:
      - .offset:         0
        .size:           128
        .value_kind:     by_value
      - .offset:         128
        .size:           4
        .value_kind:     hidden_block_count_x
      - .offset:         132
        .size:           4
        .value_kind:     hidden_block_count_y
      - .offset:         136
        .size:           4
        .value_kind:     hidden_block_count_z
      - .offset:         140
        .size:           2
        .value_kind:     hidden_group_size_x
      - .offset:         142
        .size:           2
        .value_kind:     hidden_group_size_y
      - .offset:         144
        .size:           2
        .value_kind:     hidden_group_size_z
      - .offset:         146
        .size:           2
        .value_kind:     hidden_remainder_x
      - .offset:         148
        .size:           2
        .value_kind:     hidden_remainder_y
      - .offset:         150
        .size:           2
        .value_kind:     hidden_remainder_z
      - .offset:         168
        .size:           8
        .value_kind:     hidden_global_offset_x
      - .offset:         176
        .size:           8
        .value_kind:     hidden_global_offset_y
      - .offset:         184
        .size:           8
        .value_kind:     hidden_global_offset_z
      - .offset:         192
        .size:           2
        .value_kind:     hidden_grid_dims
      - .offset:         216
        .size:           8
        .value_kind:     hidden_multigrid_sync_arg
      - .offset:         248
        .size:           4
        .value_kind:     hidden_dynamic_lds_size
    .group_segment_fixed_size: 0
    .kernarg_segment_align: 8
    .kernarg_segment_size: 384
    .language:       OpenCL C
    .language_version:
      - 2
      - 0
    .max_flat_workgroup_size: 512
    .name:           _Z4mega6Params
    .private_segment_fixed_size: 0
    .sgpr_count:     108
    .sgpr_spill_count: 146
    .symbol:         _Z4mega6Params.kd
    .uniform_work_group_size: 1
    .uses_dynamic_stack: false
    .vgpr_count:     252
    .vgpr_spill_count: 0
    .wavefront_size: 64
